# group barriers skip the L2 write-back (except boundaries 4/8/12/16) when a run-time XCC_ID check shows all 32 workgroups of the group share one XCD
# speedup vs baseline: 1.0389x; 1.0069x over previous
; DI bool sb_tile(int bid, int nb, int it, int NT, int& mt, int& nt) {
;   const int G = nb >> 3, x = bid & 7, l = bid >> 3;
;   const int s = l + it * G;
;   const int sb = (s >> 5) * 8 + x, w = s & 31;
;   if (NT == 4) {
;     if (sb >= 48) return false;
;     mt = sb * 8 + (w >> 2); nt = w & 3;
;     return true;
;   }
;   const int NG = NT >> 1;
;   if (sb >= 24 * NG) return false;
;   const int mg = sb / NG, ng = sb - mg * NG;
;   mt = mg * 16 + (w >> 1); nt = ng * 2 + (w & 1);
;   return true;
; }
; __global__ void __launch_bounds__(NTHR, 2) mega(Params p, int ph_lo, int ph_hi) {
;   __shared__ __attribute__((aligned(16))) char smem[SMEM_BYTES];
;   cg::grid_group grid = cg::this_grid();
;   for (int ph = ph_lo; ph < ph_hi; ++ph) {
;     if (ph > ph_lo) grid.sync();
;     run_phase(p, ph, smem);
_Z4mega6Paramsii:
	s_load_dwordx2 s[30:31], s[0:1], 0xa8
	s_waitcnt lgkmcnt(0)
	s_cmp_ge_i32 s30, s31
	s_cbranch_scc1 .LBB0_411
	s_load_dwordx16 s[4:19], s[0:1], 0x0
	s_load_dwordx16 s[36:51], s[0:1], 0x40
	s_load_dwordx2 s[88:89], s[0:1], 0xa0
	s_load_dwordx8 s[20:27], s[0:1], 0x80
	s_load_dword s34, s[0:1], 0xb0
	s_mov_b32 s28, s2
	s_add_u32 s2, s0, 0xb0
	s_addc_u32 s3, s1, 0
	s_mov_b32 s1, 0
	v_writelane_b32 v253, s2, 0
	s_waitcnt lgkmcnt(0)
	s_ashr_i32 s35, s34, 31
	s_cmp_lg_u64 s[34:35], 0x100
	v_writelane_b32 v253, s3, 1
	s_cselect_b64 s[52:53], -1, 0
	v_and_b32_e32 v194, 0x3ff, v0
	v_and_b32_e32 v0, 0x3fffffff, v0
	v_writelane_b32 v253, s0, 2
	s_add_u32 s54, s88, 0x304a000
	s_addc_u32 s55, s89, 0
	v_writelane_b32 v253, s1, 3
	v_cmp_eq_u32_e64 s[0:1], 0, v0
	s_cmpk_lt_i32 s28, 0xc00
	v_mbcnt_lo_u32_b32 v0, -1, 0
	v_writelane_b32 v253, s0, 4
	v_mbcnt_hi_u32_b32 v196, -1, v0
	v_and_b32_e32 v0, 64, v196
	v_writelane_b32 v253, s1, 5
	s_cselect_b64 s[0:1], -1, 0
	v_writelane_b32 v253, s0, 6
	s_cmpk_lt_i32 s28, 0x80
	s_mov_b64 s[94:95], 0x100
	v_writelane_b32 v253, s1, 7
	s_cselect_b64 s[0:1], -1, 0
	s_add_u32 s56, s88, 0x2fca000
	s_addc_u32 s57, s89, 0
	v_writelane_b32 v253, s0, 8
	s_cmpk_lt_i32 s28, 0x17f4
	v_mov_b32_e32 v1, 0
	v_writelane_b32 v253, s1, 9
	s_cselect_b64 s[0:1], -1, 0
	v_writelane_b32 v253, s0, 10
	s_cmp_lg_u64 s[48:49], 0
	s_cselect_b64 s[58:59], -1, 0
	v_writelane_b32 v253, s1, 11
	s_cmp_lg_u64 s[44:45], 0
	s_cselect_b64 s[60:61], -1, 0
	s_cmp_lg_u64 s[40:41], 0
	v_writelane_b32 v253, s36, 12
	s_cselect_b64 s[62:63], -1, 0
	s_cmp_lg_u64 s[36:37], 0
	v_writelane_b32 v253, s37, 13
	v_writelane_b32 v253, s38, 14
	v_writelane_b32 v253, s39, 15
	v_writelane_b32 v253, s40, 16
	v_writelane_b32 v253, s41, 17
	v_writelane_b32 v253, s42, 18
	v_writelane_b32 v253, s43, 19
	v_writelane_b32 v253, s44, 20
	v_writelane_b32 v253, s45, 21
	v_writelane_b32 v253, s46, 22
	v_writelane_b32 v253, s47, 23
	v_writelane_b32 v253, s48, 24
	v_writelane_b32 v253, s49, 25
	v_writelane_b32 v253, s50, 26
	v_writelane_b32 v253, s51, 27
	v_writelane_b32 v253, s4, 28
	s_cselect_b64 s[64:65], -1, 0
	s_cmp_lg_u64 s[10:11], 0
	v_writelane_b32 v253, s5, 29
	v_writelane_b32 v253, s6, 30
	v_writelane_b32 v253, s7, 31
	v_writelane_b32 v253, s8, 32
	v_writelane_b32 v253, s9, 33
	v_writelane_b32 v253, s10, 34
	v_writelane_b32 v253, s11, 35
	v_writelane_b32 v253, s12, 36
	s_cselect_b64 s[66:67], -1, 0
	s_add_u32 s68, s88, 0x2fc0000
	v_writelane_b32 v253, s13, 37
	s_addc_u32 s69, s89, 0
	v_writelane_b32 v253, s14, 38
	s_add_u32 s70, s88, 0xf04a000
	v_writelane_b32 v253, s15, 39
	s_addc_u32 s71, s89, 0
	s_ashr_i32 s0, s28, 5
	v_writelane_b32 v253, s16, 40
	s_and_b32 s72, s28, 7
	s_and_b32 s0, s0, -8
	v_writelane_b32 v253, s17, 41
	s_ashr_i32 s73, s28, 3
	s_or_b32 s2, s0, s72
	s_mul_i32 s2, s72, 6
	v_writelane_b32 v253, s18, 42
	s_cmp_lt_i32 s2, 48
	v_writelane_b32 v253, s19, 43
	s_cselect_b64 s[0:1], -1, 0
	v_writelane_b32 v253, s0, 44
	s_and_b32 s15, s73, 3
	s_mov_b32 s86, 0x358637bd
	v_writelane_b32 v253, s1, 45
	s_lshl_b32 s0, s2, 3
	s_bfe_u32 s1, s73, 0x30002
	s_or_b32 s0, s0, s1
	s_lshl_b32 s4, s0, 8
	s_ashr_i32 s5, s4, 31
	v_writelane_b32 v253, s0, 46
	s_mul_i32 s0, s0, 0x160000
	s_mul_hi_i32 s3, s4, 0x1600
	s_add_u32 s6, s70, s0
	s_addc_u32 s7, s71, s3
	v_writelane_b32 v253, s6, 47
	s_mul_i32 s1, s15, 0xb0000
	s_movk_i32 s87, 0x90
	v_writelane_b32 v253, s7, 48
	s_or_b32 s6, s4, 0x80
	s_ashr_i32 s7, s6, 31
	s_mul_i32 s3, s6, 0x1600
	s_mul_hi_i32 s0, s6, 0x1600
	s_add_u32 s8, s70, s3
	s_addc_u32 s9, s71, s0
	s_ashr_i32 s74, s34, 3
	v_writelane_b32 v253, s8, 49
	s_mul_i32 s2, s72, 37
	s_cmpk_lt_i32 s2, 0x108
	s_mul_hi_i32 s0, s2, 0x2e8ba2e9
	v_writelane_b32 v253, s9, 50
	s_cselect_b64 s[8:9], -1, 0
	s_lshr_b32 s3, s0, 31
	s_ashr_i32 s0, s0, 1
	s_add_i32 s0, s0, s3
	s_mul_i32 s3, s0, -11
	v_writelane_b32 v253, s8, 51
	s_add_i32 s3, s3, s2
	s_lshl_b32 s0, s0, 4
	s_bfe_u32 s14, s73, 0x40001
	v_writelane_b32 v253, s9, 52
	s_or_b32 s8, s0, s14
	s_lshl_b32 s0, s3, 1
	s_and_b32 s3, s73, 1
	s_or_b32 s0, s0, s3
	s_lshl_b32 s10, s0, 8
	v_writelane_b32 v253, s8, 53
	s_ashr_i32 s11, s10, 31
	s_lshl_b32 s8, s8, 8
	v_writelane_b32 v253, s0, 54
	s_lshl_b64 s[12:13], s[10:11], 11
	v_writelane_b32 v253, s12, 55
	s_ashr_i32 s9, s8, 31
	s_mov_b64 s[78:79], 0x304a100
	v_writelane_b32 v253, s13, 56
	s_lshl_b64 s[12:13], s[8:9], 11
	s_add_u32 s12, s54, s12
	s_addc_u32 s13, s55, s13
	s_bitset1_b32 s10, 7
	s_bitset1_b32 s8, 7
	s_ashr_i32 s11, s10, 31
	s_ashr_i32 s9, s8, 31
	s_lshl_b64 s[10:11], s[10:11], 11
	s_lshl_b64 s[8:9], s[8:9], 11
	s_add_u32 s8, s54, s8
	s_addc_u32 s9, s55, s9
	s_lshl_b32 s0, s15, 18
	s_lshl_b64 s[4:5], s[4:5], 11
	s_add_u32 s4, s54, s4
	s_addc_u32 s5, s55, s5
	v_writelane_b32 v254, s4, 0
	v_writelane_b32 v253, s12, 57
	s_mov_b64 s[96:97], 0x308a100
	v_writelane_b32 v254, s5, 1
	s_lshl_b64 s[4:5], s[6:7], 11
	s_add_u32 s4, s54, s4
	s_addc_u32 s5, s55, s5
	v_writelane_b32 v254, s4, 2
	v_writelane_b32 v253, s13, 58
	v_writelane_b32 v253, s10, 59
	v_writelane_b32 v254, s5, 3
	s_add_u32 s4, s88, 0x37e4a000
	s_addc_u32 s5, s89, 0
	v_writelane_b32 v254, s4, 4
	s_lshr_b32 s75, s28, 3
	v_writelane_b32 v253, s11, 60
	v_writelane_b32 v254, s5, 5
	s_lshl_b32 s4, s28, 1
	s_and_b32 s4, s4, 14
	s_ashr_i32 s5, s28, 7
	s_add_i32 s76, s4, s5
	s_add_u32 s77, s88, 0x2be4a000
	s_addc_u32 s81, s89, 0
	s_add_u32 s82, s88, 0x3064a000
	s_addc_u32 s83, s89, 0
	s_add_u32 s92, s88, 0x34e4a000
	s_addc_u32 s4, s89, 0
	v_writelane_b32 v254, s4, 6
	s_add_u32 s4, s88, 0x37e4a030
	s_addc_u32 s5, s89, 0
	v_writelane_b32 v254, s4, 7
	v_writelane_b32 v253, s8, 61
	s_mov_b64 s[90:91], 0x304a180
; DI bool sb_tile(int bid, int nb, int it, int NT, int& mt, int& nt) {
;   const int G = nb >> 3, x = bid & 7, l = bid >> 3;
;   const int s = l + it * G;
;   const int sb = (s >> 5) * 8 + x, w = s & 31;
;   if (NT == 4) {
;     if (sb >= 48) return false;
;     mt = sb * 8 + (w >> 2); nt = w & 3;
;     return true;
;   }
;   const int NG = NT >> 1;
;   if (sb >= 24 * NG) return false;
;   const int mg = sb / NG, ng = sb - mg * NG;
;   mt = mg * 16 + (w >> 1); nt = ng * 2 + (w & 1);
;   return true;
; }
; __global__ void __launch_bounds__(NTHR, 2) mega(Params p, int ph_lo, int ph_hi) {
;     ...
;   cg::grid_group grid = cg::this_grid();
;   for (int ph = ph_lo; ph < ph_hi; ++ph) {
;     if (ph > ph_lo) grid.sync();
;     run_phase(p, ph, smem);
	v_writelane_b32 v254, s5, 8
	s_add_u32 s4, s88, 0xf04a600
	v_writelane_b32 v254, s4, 9
	s_addc_u32 s4, s89, 0
	v_writelane_b32 v254, s4, 10
	s_add_u32 s4, s88, 0xf04a900
	v_writelane_b32 v254, s4, 11
	s_addc_u32 s4, s89, 0
	v_writelane_b32 v254, s4, 12
	s_add_u32 s4, s88, 0xf04a800
	v_writelane_b32 v254, s4, 13
	s_addc_u32 s4, s89, 0
	v_writelane_b32 v254, s4, 14
	s_add_u32 s4, s88, 0x37e4a010
	s_addc_u32 s5, s89, 0
	v_writelane_b32 v254, s4, 15
	v_writelane_b32 v253, s9, 62
	v_writelane_b32 v253, s15, 63
	v_writelane_b32 v254, s5, 16
	s_add_u32 s4, s88, 0xf04a200
	v_writelane_b32 v254, s4, 17
	s_addc_u32 s4, s89, 0
	v_writelane_b32 v254, s4, 18
	s_add_u32 s4, s88, 0xf04a400
	v_writelane_b32 v254, s4, 19
	s_addc_u32 s4, s89, 0
	v_writelane_b32 v254, s4, 20
	s_add_u32 s4, s88, 0xf04aa00
	v_writelane_b32 v254, s4, 21
	s_addc_u32 s4, s89, 0
	v_writelane_b32 v254, s4, 22
	s_add_u32 s4, s88, 0xf04ac00
	v_writelane_b32 v254, s4, 23
	s_addc_u32 s4, s89, 0
	v_writelane_b32 v254, s4, 24
	s_add_u32 s4, s88, 0xf04ae00
	v_writelane_b32 v254, s4, 25
	s_addc_u32 s4, s89, 0
	v_writelane_b32 v254, s4, 26
	s_add_u32 s4, s88, 0x37e4a020
	s_addc_u32 s5, s89, 0
	v_writelane_b32 v254, s4, 27
	s_cmpk_lt_i32 s28, 0x600
	s_mov_b32 s33, 0xefa18f08
	v_writelane_b32 v254, s5, 28
	s_cselect_b64 s[4:5], -1, 0
	v_writelane_b32 v254, s4, 29
	s_cmpk_lt_i32 s28, 0x300
	s_mov_b32 s80, 0x41000000
	v_writelane_b32 v254, s5, 30
	s_cselect_b64 s[4:5], -1, 0
	v_writelane_b32 v254, s4, 31
	v_add_u32_e32 v197, 64, v0
	v_xor_b32_e32 v252, 1, v196
	v_writelane_b32 v254, s5, 32
	s_add_u32 s4, s88, 0xf04b000
	s_addc_u32 s5, s89, 0
	v_writelane_b32 v254, s4, 33
	v_xor_b32_e32 v195, 2, v196
	v_xor_b32_e32 v198, 4, v196
	v_writelane_b32 v254, s5, 34
	s_add_u32 s4, s88, 0xf04b200
	s_addc_u32 s5, s89, 0
	v_writelane_b32 v254, s4, 35
	s_mul_i32 s2, s72, 17
	s_cmpk_lt_i32 s2, 0x78
	v_xor_b32_e32 v199, 8, v196
	v_writelane_b32 v254, s5, 36
	s_cselect_b64 s[4:5], -1, 0
	v_writelane_b32 v254, s4, 37
	v_xor_b32_e32 v200, 16, v196
	v_xor_b32_e32 v201, 32, v196
	v_writelane_b32 v254, s5, 38
	s_mul_hi_i32 s4, s2, 0x66666667
	s_lshr_b32 s5, s4, 31
	s_ashr_i32 s4, s4, 1
	s_add_i32 s4, s4, s5
	s_mul_i32 s5, s4, -5
	s_add_i32 s5, s5, s2
	s_lshl_b32 s2, s4, 4
	s_or_b32 s4, s2, s14
	s_lshl_b32 s2, s5, 1
	s_or_b32 s3, s2, s3
	v_writelane_b32 v254, s4, 39
	s_lshl_b32 s2, s4, 8
	s_lshl_b32 s4, s3, 8
	s_ashr_i32 s5, s4, 31
	v_writelane_b32 v254, s3, 40
	s_lshl_b64 s[6:7], s[4:5], 11
	v_writelane_b32 v254, s6, 41
	s_ashr_i32 s3, s2, 31
	s_mov_b64 s[12:13], s[20:21]
	v_writelane_b32 v254, s7, 42
	s_lshl_b64 s[6:7], s[2:3], 11
	s_add_u32 s6, s54, s6
	s_addc_u32 s7, s55, s7
	s_bitset1_b32 s4, 7
	s_bitset1_b32 s2, 7
	v_writelane_b32 v254, s6, 43
	s_ashr_i32 s5, s4, 31
	s_ashr_i32 s3, s2, 31
	v_writelane_b32 v254, s7, 44
	s_lshl_b64 s[4:5], s[4:5], 11
	s_lshl_b64 s[2:3], s[2:3], 11
	v_writelane_b32 v254, s4, 45
	s_add_u32 s2, s54, s2
	s_addc_u32 s3, s55, s3
	v_writelane_b32 v254, s5, 46
	v_writelane_b32 v254, s2, 47
	s_ashr_i32 s29, s28, 31
	s_mov_b64 s[18:19], s[26:27]
	v_writelane_b32 v254, s3, 48
	s_lshl_b64 s[2:3], s[28:29], 17
	s_add_u32 s2, s18, s2
	s_addc_u32 s3, s19, s3
	v_writelane_b32 v254, s2, 49
	s_lshl_b32 s0, s0, 1
	s_mov_b64 s[14:15], s[22:23]
	v_writelane_b32 v254, s3, 50
	s_lshl_b64 s[2:3], s[34:35], 17
	s_mov_b64 s[16:17], s[24:25]
	v_writelane_b32 v254, s2, 51
	v_writelane_b32 v255, s0, 0
	v_writelane_b32 v255, s12, 1
	v_writelane_b32 v254, s3, 52
	s_lshl_b32 s2, s28, 9
	v_writelane_b32 v254, s2, 53
	s_lshl_b32 s2, s34, 9
	v_writelane_b32 v255, s13, 2
	v_writelane_b32 v254, s2, 54
	s_lshl_b64 s[2:3], s[28:29], 5
	v_writelane_b32 v255, s14, 3
	v_writelane_b32 v254, s2, 55
	v_writelane_b32 v255, s15, 4
	v_writelane_b32 v255, s16, 5
	v_writelane_b32 v254, s3, 56
	s_lshl_b64 s[2:3], s[34:35], 5
	v_writelane_b32 v254, s2, 57
	v_writelane_b32 v255, s17, 6
	v_writelane_b32 v255, s18, 7
	v_writelane_b32 v254, s3, 58
	s_lshl_b32 s2, s28, 8
	v_writelane_b32 v254, s2, 59
	s_lshl_b32 s2, s34, 8
	v_writelane_b32 v255, s19, 8
	v_writelane_b32 v254, s2, 60
	s_lshl_b32 s2, s28, 7
	v_writelane_b32 v255, s28, 9
	s_mov_b32 s4, s30
	v_writelane_b32 v254, s2, 61
	v_writelane_b32 v255, s29, 10
	v_writelane_b32 v255, s30, 11
	s_lshl_b32 s2, s34, 7
	v_writelane_b32 v254, s2, 62
	v_writelane_b32 v255, s31, 12
	v_writelane_b32 v255, s34, 13
	s_lshl_b32 s1, s1, 1
	v_writelane_b32 v254, s1, 63
	v_writelane_b32 v255, s35, 14
	v_writelane_b32 v255, s52, 15
	s_mov_b64 s[2:3], 0x308a080
	v_mov_b32_e32 v206, 0xf149f2ca
	v_writelane_b32 v255, s53, 16
	v_writelane_b32 v255, s54, 17
	v_mov_b32_e32 v202, 0x3e38aa3b
	s_nop 0
	v_writelane_b32 v255, s55, 18
	v_writelane_b32 v255, s56, 19
	s_nop 1
	v_writelane_b32 v255, s57, 20
	v_writelane_b32 v255, s58, 21
	s_nop 1
	v_writelane_b32 v255, s59, 22
	v_writelane_b32 v255, s60, 23
	s_nop 1
	v_writelane_b32 v255, s61, 24
	v_writelane_b32 v255, s62, 25
	s_nop 1
	v_writelane_b32 v255, s63, 26
	v_writelane_b32 v255, s64, 27
	s_nop 1
	v_writelane_b32 v255, s65, 28
	v_writelane_b32 v255, s66, 29
	s_nop 1
	v_writelane_b32 v255, s67, 30
	v_writelane_b32 v255, s68, 31
	s_nop 1
	v_writelane_b32 v255, s69, 32
	v_writelane_b32 v255, s70, 33
	s_nop 1
	v_writelane_b32 v255, s71, 34
	v_writelane_b32 v255, s72, 35
	v_writelane_b32 v255, s73, 36
	v_writelane_b32 v255, s74, 37
	v_writelane_b32 v255, s75, 38
	v_writelane_b32 v255, s76, 39
	v_writelane_b32 v255, s77, 40
	v_writelane_b32 v255, s81, 41
	v_writelane_b32 v255, s82, 42
	v_writelane_b32 v255, s83, 43
	v_writelane_b32 v255, s92, 44
	s_mov_b32 s5, 0
	v_writelane_b32 v255, s5, 60
	v_writelane_b32 v255, s5, 61
	v_writelane_b32 v255, s5, 59
	v_writelane_b32 v255, s5, 62
	s_getreg_b32 s5, hwreg(HW_REG_XCC_ID)
	s_and_b32 s5, s5, 15
	s_lshl_b32 s6, s28, 2
	s_add_u32 s6, s6, 0x34e4a000
	s_add_u32 s6, s88, s6
	s_addc_u32 s7, s89, 0
	v_mov_b32_e32 v2, s5
	s_mov_b64 s[8:9], exec
	s_mov_b64 exec, 1
	global_store_dword v1, v2, s[6:7]
	s_mov_b64 exec, s[8:9]
	s_mov_b32 s5, 0
	v_writelane_b32 v255, s5, 63
	v_readfirstlane_b32 s32, v194
	s_nop 3
	s_lshr_b32 s32, s32, 8
	s_branch .LBB0_3

; __global__ void __launch_bounds__(NTHR, 2) mega(Params p, int ph_lo, int ph_hi) {
;     ...
;   cg::grid_group grid = cg::this_grid();
;   for (int ph = ph_lo; ph < ph_hi; ++ph) {
;     if (ph > ph_lo) grid.sync();
;     run_phase(p, ph, smem);
.LBB0_3:
	s_cmp_le_i32 s4, s30
	s_mov_b32 s12, 0x3a800000
	v_writelane_b32 v255, s4, 45
	s_cbranch_scc1 .LBB0_15
	s_sub_i32 s0, s4, s30
	s_cmp_lt_i32 s0, 2
	s_cbranch_scc1 .Lcg_sync
	s_waitcnt vmcnt(0) lgkmcnt(0)
	s_barrier
	s_mov_b64 s[0:1], exec
	v_readlane_b32 s6, v253, 4
	v_readlane_b32 s7, v253, 5
	s_and_b64 s[6:7], s[0:1], s[6:7]
	s_mov_b64 exec, s[6:7]
	s_cbranch_execz .Lfb_done
	v_readlane_b32 s8, v255, 63
	s_sub_i32 s9, s4, s30
	s_cmp_eq_u32 s8, 0
	s_cbranch_scc1 .Lfb_wb
	s_and_b32 s9, s9, 3
	s_cmp_lg_u32 s9, 0
	s_cbranch_scc1 .Lfb_nowb
.Lfb_wb:
	buffer_wbl2 sc1
.Lfb_nowb:
	s_sub_i32 s8, s4, s30
	v_readlane_b32 s9, v255, 13
	s_mov_b32 s10, 0x1fffc
	s_lshr_b32 s10, s10, s8
	s_and_b32 s11, s10, 1
	s_cmp_lt_i32 s8, 10
	s_cbranch_scc0 .Lfb_usey
	s_cmp_eq_u32 s11, 0
	s_cbranch_scc0 .Lfb_xl
	v_readlane_b32 s8, v255, 61
	s_add_i32 s8, s8, 1
	s_mov_b32 s10, 0x1cc2000
	v_writelane_b32 v255, s8, 61
	s_branch .Lfb_go

; __global__ void __launch_bounds__(NTHR, 2) mega(Params p, int ph_lo, int ph_hi) {
;     ...
;   cg::grid_group grid = cg::this_grid();
;   for (int ph = ph_lo; ph < ph_hi; ++ph) {
;     if (ph > ph_lo) grid.sync();
;     run_phase(p, ph, smem);
.LBB0_14:
	s_or_b64 exec, exec, s[0:1]
	v_readlane_b32 s4, v255, 45
	s_barrier
	s_getreg_b32 s5, hwreg(HW_REG_XCC_ID)
	s_and_b32 s5, s5, 15
	v_readlane_b32 s6, v255, 9
	s_and_b32 s6, s6, 7
	v_and_b32_e32 v2, 31, v196
	v_lshl_add_u32 v2, v2, 3, s6
	v_lshlrev_b32_e32 v2, 2, v2
	s_add_u32 s6, s88, 0x34e4a000
	s_addc_u32 s7, s89, 0
	global_load_dword v3, v2, s[6:7]
	s_waitcnt vmcnt(0)
	v_cmp_ne_u32_e32 vcc, s5, v3
	s_nop 1
	s_cmp_eq_u64 vcc, 0
	s_cselect_b32 s5, 1, 0
	v_writelane_b32 v255, s5, 63
